# P1 GEMM on 240 WGs, 16 converter WGs run 18432 deferred items (144/wave); PLE GEMM in P3b
# baseline (speedup 1.0000x reference)
.LBB0_9:
	s_cmp_lg_u32 s101, 0
	s_cbranch_scc1 .Lcv_go
	s_cmp_lt_i32 s80, 0x16280
	s_cbranch_scc1 .Lcv_go
	s_cmp_lt_i32 s80, 0x1aa80
	s_cbranch_scc1 .LBB0_8

.LBB0_399:
	s_cmpk_eq_i32 s88, 0x100
	s_cselect_b64 s[0:1], -1, 0
	s_cmpk_lg_i32 s88, 0x100
	v_writelane_b32 v250, s0, 23
	s_cselect_b64 s[22:23], -1, 0
	s_cmp_lt_i32 s2, s99
	v_writelane_b32 v250, s1, 24
	s_cselect_b64 s[0:1], -1, 0
	s_or_b64 s[0:1], s[0:1], s[22:23]
	s_and_b64 vcc, exec, s[0:1]
	s_cbranch_vccnz .LBB0_416
	v_writelane_b32 v248, s0, 0
	v_writelane_b32 v248, s1, 1
	v_writelane_b32 v248, s2, 2
	v_writelane_b32 v248, s3, 3
	v_writelane_b32 v248, s4, 4
	v_writelane_b32 v248, s5, 5
	v_writelane_b32 v248, s6, 6
	v_writelane_b32 v248, s7, 7
	v_writelane_b32 v248, s8, 8
	v_writelane_b32 v248, s9, 9
	v_writelane_b32 v248, s10, 10
	v_writelane_b32 v248, s11, 11
	v_writelane_b32 v248, s12, 12
	v_writelane_b32 v248, s13, 13
	v_writelane_b32 v248, s14, 14
	v_writelane_b32 v248, s15, 15
	v_writelane_b32 v248, s16, 16
	v_writelane_b32 v248, s17, 17
	v_writelane_b32 v248, s18, 18
	v_writelane_b32 v248, s19, 19
	v_writelane_b32 v248, s20, 20
	v_writelane_b32 v248, s21, 21
	v_writelane_b32 v248, s22, 22
	v_writelane_b32 v248, s23, 23
	v_writelane_b32 v248, s24, 24
	v_writelane_b32 v248, s25, 25
	v_writelane_b32 v248, s26, 26
	v_writelane_b32 v248, s27, 27
	v_writelane_b32 v248, s28, 28
	v_writelane_b32 v248, s29, 29
	v_writelane_b32 v248, s30, 30
	v_writelane_b32 v248, s31, 31
	v_writelane_b32 v248, s32, 32
	v_writelane_b32 v248, s33, 33
	v_writelane_b32 v248, s34, 34
	v_writelane_b32 v248, s35, 35
	v_writelane_b32 v248, s36, 36
	v_writelane_b32 v248, s37, 37
	v_writelane_b32 v248, s38, 38
	v_writelane_b32 v248, s39, 39
	v_writelane_b32 v248, s40, 40
	v_writelane_b32 v248, s41, 41
	v_writelane_b32 v248, s42, 42
	v_writelane_b32 v248, s43, 43
	v_writelane_b32 v248, s44, 44
	v_writelane_b32 v248, s45, 45
	v_writelane_b32 v248, s46, 46
	v_writelane_b32 v248, s47, 47
	v_writelane_b32 v248, s48, 48
	v_writelane_b32 v248, s49, 49
	v_writelane_b32 v248, s50, 50
	v_writelane_b32 v248, s51, 51
	v_writelane_b32 v248, s52, 52
	v_writelane_b32 v248, s53, 53
	v_writelane_b32 v248, s54, 54
	v_writelane_b32 v248, s55, 55
	v_writelane_b32 v248, s56, 56
	v_writelane_b32 v248, s57, 57
	v_writelane_b32 v248, s58, 58
	v_writelane_b32 v248, s59, 59
	v_writelane_b32 v248, s60, 60
	v_writelane_b32 v248, s61, 61
	v_writelane_b32 v248, s62, 62
	v_writelane_b32 v248, s63, 63
	v_writelane_b32 v249, s64, 0
	v_writelane_b32 v249, s65, 1
	v_writelane_b32 v249, s66, 2
	v_writelane_b32 v249, s67, 3
	v_writelane_b32 v249, s68, 4
	v_writelane_b32 v249, s69, 5
	v_writelane_b32 v249, s70, 6
	v_writelane_b32 v249, s71, 7
	v_writelane_b32 v249, s72, 8
	v_writelane_b32 v249, s73, 9
	v_writelane_b32 v249, s74, 10
	v_writelane_b32 v249, s75, 11
	v_writelane_b32 v249, s76, 12
	v_writelane_b32 v249, s77, 13
	v_writelane_b32 v249, s78, 14
	v_writelane_b32 v249, s79, 15
	v_writelane_b32 v249, s80, 16
	v_writelane_b32 v249, s81, 17
	v_writelane_b32 v249, s82, 18
	v_writelane_b32 v249, s83, 19
	v_writelane_b32 v249, s84, 20
	v_writelane_b32 v249, s85, 21
	v_writelane_b32 v249, s86, 22
	v_writelane_b32 v249, s87, 23
	v_writelane_b32 v249, s88, 24
	v_writelane_b32 v249, s89, 25
	v_writelane_b32 v249, s90, 26
	v_writelane_b32 v249, s91, 27
	v_writelane_b32 v249, s92, 28
	v_writelane_b32 v249, s93, 29
	v_writelane_b32 v249, s94, 30
	v_writelane_b32 v249, s95, 31
	v_writelane_b32 v249, s96, 32
	v_writelane_b32 v249, s97, 33
	v_readlane_b32 s1, v250, 9
	v_readlane_b32 s86, v250, 10
	v_readlane_b32 s87, v250, 11
	s_sub_i32 s0, s2, s99
	s_lshl_b32 s0, s0, 3
	s_nop 1
	s_add_i32 s12, s0, s1
	s_add_i32 s12, s12, 0x16280
	s_movk_i32 s14, 0x80
	s_mov_b32 s100, 0x1aa80
	s_mov_b32 s101, 1
	s_branch .Lcv_entry
